# v031 with 16 bytes of unreachable padding before the Fourier-2 setup (placement scan)
# baseline (speedup 1.0000x reference)
.LBB0_713:
	s_andn2_b64 vcc, exec, s[76:77]
	s_waitcnt vmcnt(0) lgkmcnt(0)
	s_barrier
	s_cbranch_vccnz .LBB0_656
	ds_read2st64_b32 v[66:67], v64 offset1:1
	ds_read2st64_b32 v[76:77], v64 offset0:2 offset1:3
	ds_read2st64_b32 v[78:79], v64 offset0:4 offset1:5
	ds_read2st64_b32 v[80:81], v64 offset0:6 offset1:7
	ds_read2st64_b32 v[82:83], v64 offset0:8 offset1:9
	ds_read2st64_b32 v[84:85], v64 offset0:10 offset1:11
	ds_read2st64_b32 v[86:87], v64 offset0:12 offset1:13
	ds_read2st64_b32 v[88:89], v64 offset0:14 offset1:15
	ds_read2st64_b32 v[90:91], v64 offset0:16 offset1:17
	ds_read2st64_b32 v[116:117], v64 offset0:18 offset1:19
	ds_read2st64_b32 v[118:119], v64 offset0:20 offset1:21
	ds_read2st64_b32 v[120:121], v64 offset0:22 offset1:23
	ds_read2st64_b32 v[122:123], v64 offset0:24 offset1:25
	ds_read2st64_b32 v[124:125], v64 offset0:26 offset1:27
	ds_read2st64_b32 v[126:127], v64 offset0:28 offset1:29
	ds_read2st64_b32 v[128:129], v64 offset0:30 offset1:31
	ds_read2st64_b32 v[130:131], v64 offset0:32 offset1:33
	ds_read2st64_b32 v[132:133], v64 offset0:34 offset1:35
	ds_read2st64_b32 v[134:135], v64 offset0:36 offset1:37
	ds_read2st64_b32 v[136:137], v64 offset0:38 offset1:39
	ds_read2st64_b32 v[138:139], v64 offset0:40 offset1:41
	ds_read2st64_b32 v[140:141], v64 offset0:42 offset1:43
	ds_read2st64_b32 v[142:143], v64 offset0:44 offset1:45
	ds_read2st64_b32 v[148:149], v64 offset0:46 offset1:47
	ds_read2st64_b32 v[68:69], v64 offset0:58 offset1:59
	ds_read2st64_b32 v[150:151], v64 offset0:48 offset1:49
	ds_read2st64_b32 v[152:153], v64 offset0:50 offset1:51
	ds_read2st64_b32 v[154:155], v64 offset0:52 offset1:53
	ds_read2st64_b32 v[156:157], v64 offset0:54 offset1:55
	ds_read2st64_b32 v[72:73], v64 offset0:60 offset1:61
	ds_read2st64_b32 v[96:97], v64 offset0:62 offset1:63
	ds_read2st64_b32 v[162:163], v64 offset0:56 offset1:57
	s_waitcnt lgkmcnt(14)
	v_pk_fma_f32 v[98:99], v[50:51], v[74:75], v[76:77] op_sel_hi:[1,0,1] neg_lo:[0,0,1] neg_hi:[0,0,1]
	v_pk_fma_f32 v[104:105], v[48:49], v[74:75], v[66:67] op_sel_hi:[1,0,1] neg_lo:[0,0,1] neg_hi:[0,0,1]
	global_load_dwordx4 v[64:67], v146, s[30:31]
	global_load_dwordx4 v[48:51], v146, s[30:31] offset:32
	v_pk_mul_f32 v[164:165], v[104:105], v[104:105]
	s_waitcnt lgkmcnt(7)
	v_pk_fma_f32 v[70:71], v[26:27], v[74:75], v[68:69] op_sel_hi:[1,0,1] neg_lo:[0,0,1] neg_hi:[0,0,1]
	s_waitcnt lgkmcnt(2)
	v_pk_fma_f32 v[68:69], v[28:29], v[74:75], v[72:73] op_sel_hi:[1,0,1] neg_lo:[0,0,1] neg_hi:[0,0,1]
	s_waitcnt lgkmcnt(1)
	v_pk_fma_f32 v[72:73], v[30:31], v[74:75], v[96:97] op_sel_hi:[1,0,1] neg_lo:[0,0,1] neg_hi:[0,0,1]
	v_or_b32_e32 v26, s34, v161
	v_pk_mul_f32 v[160:161], v[98:99], v[98:99]
	v_pk_fma_f32 v[102:103], v[54:55], v[74:75], v[80:81] op_sel_hi:[1,0,1] neg_lo:[0,0,1] neg_hi:[0,0,1]
	v_pk_fma_f32 v[108:109], v[52:53], v[74:75], v[78:79] op_sel_hi:[1,0,1] neg_lo:[0,0,1] neg_hi:[0,0,1]
	v_pk_fma_f32 v[106:107], v[58:59], v[74:75], v[84:85] op_sel_hi:[1,0,1] neg_lo:[0,0,1] neg_hi:[0,0,1]
	v_pk_fma_f32 v[112:113], v[56:57], v[74:75], v[82:83] op_sel_hi:[1,0,1] neg_lo:[0,0,1] neg_hi:[0,0,1]
	v_pk_fma_f32 v[110:111], v[62:63], v[74:75], v[88:89] op_sel_hi:[1,0,1] neg_lo:[0,0,1] neg_hi:[0,0,1]
	v_pk_fma_f32 v[114:115], v[60:61], v[74:75], v[86:87] op_sel_hi:[1,0,1] neg_lo:[0,0,1] neg_hi:[0,0,1]
	v_pk_fma_f32 v[60:61], v[2:3], v[74:75], v[116:117] op_sel_hi:[1,0,1] neg_lo:[0,0,1] neg_hi:[0,0,1]
	v_pk_fma_f32 v[62:63], v[0:1], v[74:75], v[90:91] op_sel_hi:[1,0,1] neg_lo:[0,0,1] neg_hi:[0,0,1]
	v_pk_fma_f32 v[76:77], v[6:7], v[74:75], v[120:121] op_sel_hi:[1,0,1] neg_lo:[0,0,1] neg_hi:[0,0,1]
	v_pk_fma_f32 v[80:81], v[4:5], v[74:75], v[118:119] op_sel_hi:[1,0,1] neg_lo:[0,0,1] neg_hi:[0,0,1]
	v_pk_fma_f32 v[78:79], v[10:11], v[74:75], v[124:125] op_sel_hi:[1,0,1] neg_lo:[0,0,1] neg_hi:[0,0,1]
	v_pk_fma_f32 v[82:83], v[8:9], v[74:75], v[122:123] op_sel_hi:[1,0,1] neg_lo:[0,0,1] neg_hi:[0,0,1]
	v_pk_fma_f32 v[84:85], v[14:15], v[74:75], v[128:129] op_sel_hi:[1,0,1] neg_lo:[0,0,1] neg_hi:[0,0,1]
	v_pk_fma_f32 v[86:87], v[12:13], v[74:75], v[126:127] op_sel_hi:[1,0,1] neg_lo:[0,0,1] neg_hi:[0,0,1]
	v_pk_fma_f32 v[34:35], v[34:35], v[74:75], v[132:133] op_sel_hi:[1,0,1] neg_lo:[0,0,1] neg_hi:[0,0,1]
	v_pk_fma_f32 v[88:89], v[32:33], v[74:75], v[130:131] op_sel_hi:[1,0,1] neg_lo:[0,0,1] neg_hi:[0,0,1]
	v_pk_fma_f32 v[38:39], v[38:39], v[74:75], v[136:137] op_sel_hi:[1,0,1] neg_lo:[0,0,1] neg_hi:[0,0,1]
	v_pk_fma_f32 v[90:91], v[36:37], v[74:75], v[134:135] op_sel_hi:[1,0,1] neg_lo:[0,0,1] neg_hi:[0,0,1]
	v_pk_fma_f32 v[36:37], v[42:43], v[74:75], v[140:141] op_sel_hi:[1,0,1] neg_lo:[0,0,1] neg_hi:[0,0,1]
	v_pk_fma_f32 v[42:43], v[40:41], v[74:75], v[138:139] op_sel_hi:[1,0,1] neg_lo:[0,0,1] neg_hi:[0,0,1]
	v_pk_fma_f32 v[40:41], v[46:47], v[74:75], v[148:149] op_sel_hi:[1,0,1] neg_lo:[0,0,1] neg_hi:[0,0,1]
	v_pk_fma_f32 v[44:45], v[44:45], v[74:75], v[142:143] op_sel_hi:[1,0,1] neg_lo:[0,0,1] neg_hi:[0,0,1]
	v_pk_fma_f32 v[18:19], v[18:19], v[74:75], v[152:153] op_sel_hi:[1,0,1] neg_lo:[0,0,1] neg_hi:[0,0,1]
	v_pk_fma_f32 v[46:47], v[16:17], v[74:75], v[150:151] op_sel_hi:[1,0,1] neg_lo:[0,0,1] neg_hi:[0,0,1]
	v_pk_fma_f32 v[16:17], v[22:23], v[74:75], v[156:157] op_sel_hi:[1,0,1] neg_lo:[0,0,1] neg_hi:[0,0,1]
	v_pk_fma_f32 v[20:21], v[20:21], v[74:75], v[154:155] op_sel_hi:[1,0,1] neg_lo:[0,0,1] neg_hi:[0,0,1]
	s_waitcnt lgkmcnt(0)
	v_pk_fma_f32 v[22:23], v[24:25], v[74:75], v[162:163] op_sel_hi:[1,0,1] neg_lo:[0,0,1] neg_hi:[0,0,1]
	v_add_f32_e32 v74, v164, v165
	v_add_f32_e32 v74, v74, v160
	v_pk_mul_f32 v[168:169], v[108:109], v[108:109]
	v_add_f32_e32 v74, v74, v161
	v_add_f32_e32 v74, v74, v168
	v_pk_mul_f32 v[166:167], v[102:103], v[102:103]
	v_add_f32_e32 v74, v74, v169
	global_load_dwordx4 v[56:59], v146, s[30:31] offset:64
	global_load_dwordx4 v[52:55], v146, s[30:31] offset:96
	v_add_f32_e32 v74, v74, v166
	v_pk_mul_f32 v[172:173], v[112:113], v[112:113]
	v_add_f32_e32 v74, v74, v167
	v_add_f32_e32 v74, v74, v172
	v_pk_mul_f32 v[170:171], v[106:107], v[106:107]
	v_add_f32_e32 v74, v74, v173
	v_add_f32_e32 v74, v74, v170
	v_pk_mul_f32 v[178:179], v[114:115], v[114:115]
	v_add_f32_e32 v74, v74, v171
	v_add_f32_e32 v74, v74, v178
	v_pk_mul_f32 v[174:175], v[110:111], v[110:111]
	v_add_f32_e32 v74, v74, v179
	v_add_f32_e32 v74, v74, v174
	v_pk_mul_f32 v[180:181], v[62:63], v[62:63]
	v_add_f32_e32 v74, v74, v175
	v_add_f32_e32 v74, v74, v180
	v_pk_mul_f32 v[116:117], v[60:61], v[60:61]
	v_add_f32_e32 v74, v74, v181
	v_add_f32_e32 v74, v74, v116
	v_pk_mul_f32 v[118:119], v[80:81], v[80:81]
	v_add_f32_e32 v74, v74, v117
	v_add_f32_e32 v74, v74, v118
	v_pk_mul_f32 v[120:121], v[76:77], v[76:77]
	v_add_f32_e32 v74, v74, v119
	v_add_f32_e32 v74, v74, v120
	v_pk_mul_f32 v[122:123], v[82:83], v[82:83]
	v_add_f32_e32 v74, v74, v121
	v_add_f32_e32 v74, v74, v122
	v_pk_mul_f32 v[124:125], v[78:79], v[78:79]
	v_add_f32_e32 v74, v74, v123
	v_add_f32_e32 v74, v74, v124
	v_pk_mul_f32 v[126:127], v[86:87], v[86:87]
	v_add_f32_e32 v74, v74, v125
	v_add_f32_e32 v74, v74, v126
	v_pk_mul_f32 v[128:129], v[84:85], v[84:85]
	v_add_f32_e32 v74, v74, v127
	v_add_f32_e32 v74, v74, v128
	v_pk_mul_f32 v[130:131], v[88:89], v[88:89]
	v_add_f32_e32 v74, v74, v129
	v_add_f32_e32 v74, v74, v130
	v_pk_mul_f32 v[132:133], v[34:35], v[34:35]
	v_add_f32_e32 v74, v74, v131
	v_add_f32_e32 v74, v74, v132
	v_pk_mul_f32 v[134:135], v[90:91], v[90:91]
	v_add_f32_e32 v74, v74, v133
	v_add_f32_e32 v74, v74, v134
	v_pk_mul_f32 v[136:137], v[38:39], v[38:39]
	v_add_f32_e32 v74, v74, v135
	v_add_f32_e32 v74, v74, v136
	v_pk_mul_f32 v[138:139], v[42:43], v[42:43]
	v_add_f32_e32 v74, v74, v137
	v_add_f32_e32 v74, v74, v138
	v_pk_mul_f32 v[140:141], v[36:37], v[36:37]
	v_add_f32_e32 v74, v74, v139
	v_add_f32_e32 v74, v74, v140
	v_pk_mul_f32 v[142:143], v[44:45], v[44:45]
	v_add_f32_e32 v74, v74, v141
	v_add_f32_e32 v74, v74, v142
	v_pk_mul_f32 v[148:149], v[40:41], v[40:41]
	v_add_f32_e32 v74, v74, v143
	v_add_f32_e32 v74, v74, v148
	v_pk_mul_f32 v[150:151], v[46:47], v[46:47]
	v_add_f32_e32 v74, v74, v149
	v_add_f32_e32 v74, v74, v150
	v_pk_mul_f32 v[152:153], v[18:19], v[18:19]
	v_add_f32_e32 v74, v74, v151
	v_add_f32_e32 v74, v74, v152
	v_pk_mul_f32 v[154:155], v[20:21], v[20:21]
	v_add_f32_e32 v74, v74, v153
	v_add_f32_e32 v74, v74, v154
	v_pk_mul_f32 v[156:157], v[16:17], v[16:17]
	v_add_f32_e32 v74, v74, v155
	v_ashrrev_i32_e32 v27, 31, v26
	v_readlane_b32 s0, v255, 20
	v_add_f32_e32 v74, v74, v156
	v_lshlrev_b64 v[26:27], 12, v[26:27]
	v_readlane_b32 s1, v255, 21
	v_pk_mul_f32 v[24:25], v[22:23], v[22:23]
	v_add_f32_e32 v74, v74, v157
	v_lshl_add_u64 v[26:27], s[0:1], 0, v[26:27]
	v_add_f32_e32 v24, v74, v24
	v_pk_mul_f32 v[92:93], v[70:71], v[70:71]
	v_lshl_add_u64 v[100:101], v[26:27], 0, s[72:73]
	global_load_dwordx4 v[26:29], v146, s[30:31] offset:128
	global_load_dwordx4 v[0:3], v146, s[30:31] offset:160
	v_add_f32_e32 v24, v24, v25
	v_add_f32_e32 v24, v24, v92
	v_pk_mul_f32 v[94:95], v[68:69], v[68:69]
	v_add_f32_e32 v24, v24, v93
	v_add_f32_e32 v24, v24, v94
	v_pk_mul_f32 v[96:97], v[72:73], v[72:73]
	v_add_f32_e32 v24, v24, v95
	v_add_f32_e32 v24, v24, v96
	v_add_f32_e32 v74, v24, v97
	ds_bpermute_b32 v75, v75, v74
	global_load_dwordx4 v[8:11], v146, s[30:31] offset:192
	global_load_dwordx4 v[4:7], v146, s[30:31] offset:224
	global_load_dwordx4 v[30:33], v146, s[30:31] offset:256
	global_load_dwordx4 v[12:15], v146, s[30:31] offset:288
	global_load_dwordx4 v[92:95], v146, s[30:31] offset:320
	global_load_dwordx4 v[116:119], v146, s[30:31] offset:352
	v_lshlrev_b32_e32 v176, 3, v158
	s_waitcnt lgkmcnt(0)
	v_add_f32_e32 v74, v74, v75
	v_fmamk_f32 v74, v74, 0x3c000000, v213
	v_rsq_f32_e32 v74, v74
	v_lshl_add_u64 v[24:25], v[100:101], 0, v[176:177]
	global_load_dwordx4 v[120:123], v146, s[30:31] offset:384
	global_load_dwordx4 v[124:127], v146, s[30:31] offset:416
	global_load_dwordx4 v[128:131], v146, s[30:31] offset:448
	v_mul_f32_e32 v74, v145, v74
	v_pk_mul_f32 v[96:97], v[104:105], v[74:75] op_sel_hi:[1,0]
	s_waitcnt vmcnt(14)
	v_pk_mul_f32 v[64:65], v[64:65], v[96:97]
	v_pk_mul_f32 v[96:97], v[98:99], v[74:75] op_sel_hi:[1,0]
	v_cvt_pk_bf16_f32 v64, v64, v65
	v_pk_mul_f32 v[66:67], v[66:67], v[96:97]
	s_nop 0
	v_cvt_pk_bf16_f32 v65, v66, v67
	global_store_dwordx2 v[24:25], v[64:65], off
	v_pk_mul_f32 v[64:65], v[108:109], v[74:75] op_sel_hi:[1,0]
	s_waitcnt vmcnt(14)
	v_pk_mul_f32 v[48:49], v[48:49], v[64:65]
	v_pk_mul_f32 v[64:65], v[102:103], v[74:75] op_sel_hi:[1,0]
	v_cvt_pk_bf16_f32 v48, v48, v49
	v_pk_mul_f32 v[50:51], v[50:51], v[64:65]
	s_nop 0
	v_cvt_pk_bf16_f32 v49, v50, v51
	global_store_dwordx2 v[24:25], v[48:49], off offset:16
	v_pk_mul_f32 v[48:49], v[112:113], v[74:75] op_sel_hi:[1,0]
	v_pk_mul_f32 v[50:51], v[106:107], v[74:75] op_sel_hi:[1,0]
	s_waitcnt vmcnt(14)
	v_pk_mul_f32 v[48:49], v[56:57], v[48:49]
	v_pk_mul_f32 v[50:51], v[58:59], v[50:51]
	v_cvt_pk_bf16_f32 v48, v48, v49
	v_cvt_pk_bf16_f32 v49, v50, v51
	global_store_dwordx2 v[24:25], v[48:49], off offset:32
	v_pk_mul_f32 v[48:49], v[114:115], v[74:75] op_sel_hi:[1,0]
	s_waitcnt vmcnt(14)
	v_pk_mul_f32 v[48:49], v[52:53], v[48:49]
	s_nop 0
	v_cvt_pk_bf16_f32 v52, v48, v49
	v_pk_mul_f32 v[48:49], v[110:111], v[74:75] op_sel_hi:[1,0]
	s_nop 0
	v_pk_mul_f32 v[48:49], v[54:55], v[48:49]
	s_nop 0
	v_cvt_pk_bf16_f32 v53, v48, v49
	global_load_dwordx4 v[48:51], v146, s[30:31] offset:480
	s_nop 0
	global_store_dwordx2 v[24:25], v[52:53], off offset:48
	v_pk_mul_f32 v[52:53], v[62:63], v[74:75] op_sel_hi:[1,0]
	s_waitcnt vmcnt(15)
	v_pk_mul_f32 v[26:27], v[52:53], v[26:27]
	v_pk_mul_f32 v[52:53], v[60:61], v[74:75] op_sel_hi:[1,0]
	v_cvt_pk_bf16_f32 v26, v26, v27
	v_pk_mul_f32 v[28:29], v[52:53], v[28:29]
	s_nop 0
	v_cvt_pk_bf16_f32 v27, v28, v29
	global_store_dwordx2 v[24:25], v[26:27], off offset:64
	v_pk_mul_f32 v[26:27], v[80:81], v[74:75] op_sel_hi:[1,0]
	s_waitcnt vmcnt(15)
	v_pk_mul_f32 v[0:1], v[26:27], v[0:1]
	v_pk_mul_f32 v[26:27], v[76:77], v[74:75] op_sel_hi:[1,0]
	v_cvt_pk_bf16_f32 v0, v0, v1
	v_pk_mul_f32 v[2:3], v[26:27], v[2:3]
	s_nop 0
	v_cvt_pk_bf16_f32 v1, v2, v3
	global_store_dwordx2 v[24:25], v[0:1], off offset:80
	v_pk_mul_f32 v[0:1], v[82:83], v[74:75] op_sel_hi:[1,0]
	v_pk_mul_f32 v[2:3], v[78:79], v[74:75] op_sel_hi:[1,0]
	s_waitcnt vmcnt(15)
	v_pk_mul_f32 v[0:1], v[0:1], v[8:9]
	v_pk_mul_f32 v[2:3], v[2:3], v[10:11]
	v_cvt_pk_bf16_f32 v0, v0, v1
	v_cvt_pk_bf16_f32 v1, v2, v3
	global_store_dwordx2 v[24:25], v[0:1], off offset:96
	v_pk_mul_f32 v[0:1], v[86:87], v[74:75] op_sel_hi:[1,0]
	v_pk_mul_f32 v[2:3], v[84:85], v[74:75] op_sel_hi:[1,0]
	s_waitcnt vmcnt(15)
	v_pk_mul_f32 v[0:1], v[0:1], v[4:5]
	v_pk_mul_f32 v[2:3], v[2:3], v[6:7]
	v_cvt_pk_bf16_f32 v0, v0, v1
	v_cvt_pk_bf16_f32 v1, v2, v3
	global_store_dwordx2 v[24:25], v[0:1], off offset:112
	v_pk_mul_f32 v[0:1], v[88:89], v[74:75] op_sel_hi:[1,0]
	v_pk_mul_f32 v[2:3], v[34:35], v[74:75] op_sel_hi:[1,0]
	s_waitcnt vmcnt(15)
	v_pk_mul_f32 v[0:1], v[0:1], v[30:31]
	v_pk_mul_f32 v[2:3], v[2:3], v[32:33]
	v_cvt_pk_bf16_f32 v0, v0, v1
	v_cvt_pk_bf16_f32 v1, v2, v3
	global_store_dwordx2 v[24:25], v[0:1], off offset:128
	v_pk_mul_f32 v[0:1], v[90:91], v[74:75] op_sel_hi:[1,0]
	v_pk_mul_f32 v[2:3], v[38:39], v[74:75] op_sel_hi:[1,0]
	s_waitcnt vmcnt(15)
	v_pk_mul_f32 v[0:1], v[0:1], v[12:13]
	v_pk_mul_f32 v[2:3], v[2:3], v[14:15]
	v_cvt_pk_bf16_f32 v0, v0, v1
	v_cvt_pk_bf16_f32 v1, v2, v3
	global_store_dwordx2 v[24:25], v[0:1], off offset:144
	v_pk_mul_f32 v[0:1], v[42:43], v[74:75] op_sel_hi:[1,0]
	v_pk_mul_f32 v[2:3], v[36:37], v[74:75] op_sel_hi:[1,0]
	s_waitcnt vmcnt(15)
	v_pk_mul_f32 v[0:1], v[0:1], v[92:93]
	v_pk_mul_f32 v[2:3], v[2:3], v[94:95]
	v_cvt_pk_bf16_f32 v0, v0, v1
	v_cvt_pk_bf16_f32 v1, v2, v3
	global_store_dwordx2 v[24:25], v[0:1], off offset:160
	v_pk_mul_f32 v[0:1], v[44:45], v[74:75] op_sel_hi:[1,0]
	v_pk_mul_f32 v[2:3], v[40:41], v[74:75] op_sel_hi:[1,0]
	s_waitcnt vmcnt(15)
	v_pk_mul_f32 v[0:1], v[0:1], v[116:117]
	v_pk_mul_f32 v[2:3], v[2:3], v[118:119]
	v_cvt_pk_bf16_f32 v0, v0, v1
	v_cvt_pk_bf16_f32 v1, v2, v3
	global_store_dwordx2 v[24:25], v[0:1], off offset:176
	v_pk_mul_f32 v[0:1], v[46:47], v[74:75] op_sel_hi:[1,0]
	v_pk_mul_f32 v[2:3], v[18:19], v[74:75] op_sel_hi:[1,0]
	s_waitcnt vmcnt(15)
	v_pk_mul_f32 v[0:1], v[0:1], v[120:121]
	v_pk_mul_f32 v[2:3], v[2:3], v[122:123]
	v_cvt_pk_bf16_f32 v0, v0, v1
	v_cvt_pk_bf16_f32 v1, v2, v3
	global_store_dwordx2 v[24:25], v[0:1], off offset:192
	v_pk_mul_f32 v[0:1], v[20:21], v[74:75] op_sel_hi:[1,0]
	v_pk_mul_f32 v[2:3], v[16:17], v[74:75] op_sel_hi:[1,0]
	s_waitcnt vmcnt(15)
	v_pk_mul_f32 v[0:1], v[0:1], v[124:125]
	v_pk_mul_f32 v[2:3], v[2:3], v[126:127]
	v_cvt_pk_bf16_f32 v0, v0, v1
	v_cvt_pk_bf16_f32 v1, v2, v3
	global_store_dwordx2 v[24:25], v[0:1], off offset:208
	v_pk_mul_f32 v[0:1], v[22:23], v[74:75] op_sel_hi:[1,0]
	v_pk_mul_f32 v[2:3], v[70:71], v[74:75] op_sel_hi:[1,0]
	s_waitcnt vmcnt(15)
	v_pk_mul_f32 v[0:1], v[0:1], v[128:129]
	v_pk_mul_f32 v[2:3], v[2:3], v[130:131]
	v_cvt_pk_bf16_f32 v0, v0, v1
	v_cvt_pk_bf16_f32 v1, v2, v3
	global_store_dwordx2 v[24:25], v[0:1], off offset:224
	v_pk_mul_f32 v[0:1], v[68:69], v[74:75] op_sel_hi:[1,0]
	v_pk_mul_f32 v[2:3], v[72:73], v[74:75] op_sel_hi:[1,0]
	s_waitcnt vmcnt(12)
	v_pk_mul_f32 v[0:1], v[0:1], v[48:49]
	v_pk_mul_f32 v[2:3], v[2:3], v[50:51]
	v_cvt_pk_bf16_f32 v0, v0, v1
	v_cvt_pk_bf16_f32 v1, v2, v3
	global_store_dwordx2 v[24:25], v[0:1], off offset:240
	s_branch .LBB0_656
	s_nop 0
	s_nop 0
	s_nop 0
	s_nop 0
